# code placement: scan compute loop head aligned to a 64-byte boundary
# baseline (speedup 1.0000x reference)
.LBB0_1047:
	s_and_b64 vcc, exec, s[24:25]
	s_cbranch_vccz .LBB0_1279
	s_waitcnt vmcnt(0)
	v_mov_b32_e32 v4, v232
	s_nop 0
	v_ashrrev_i32_e32 v0, 6, v4
	v_and_b32_e32 v54, 15, v4
	v_cmp_gt_i32_e32 vcc, 4, v0
	v_lshlrev_b32_e32 v38, 2, v54
	s_barrier
	s_and_saveexec_b64 s[24:25], vcc
	s_xor_b64 s[24:25], exec, s[24:25]
	s_cbranch_execz .LBB0_1051
	v_lshlrev_b32_e32 v2, 2, v4
	s_waitcnt lgkmcnt(0)
	s_barrier
	v_and_b32_e32 v2, 0xc0, v2
	v_lshl_or_b32 v85, v0, 8, v2
	v_mov_b32_e32 v74, 0
	v_lshlrev_b32_e32 v83, 4, v54
	v_add3_u32 v87, 0, v85, v38
	s_mov_b32 s26, 0
	s_mov_b32 s96, 0x12800
	v_mov_b32_e32 v75, v74
	v_mov_b32_e32 v76, v74
	v_mov_b32_e32 v77, v74
	v_add_u32_e32 v88, 0x12800, v83
	ds_read_b128 v[108:111], v88 offset:4096
	ds_read_b128 v[100:103], v88
	ds_read_b128 v[120:123], v88 offset:8192
	ds_read_b128 v[112:115], v88 offset:4352
	ds_read_b128 v[104:107], v88 offset:256
	ds_read_b128 v[128:131], v88 offset:8448
	ds_read_b128 v[124:127], v88 offset:4608
	ds_read_b128 v[116:119], v88 offset:512
	s_waitcnt lgkmcnt(0)
	s_and_b32 s2, s26, 1
	s_mul_i32 s3, s2, 0x5400
	v_lshlrev_b32_e32 v91, 2, v87
	v_lshl_add_u32 v91, s2, 14, v91
	s_add_i32 s2, s3, 0
	v_add_u32_e32 v0, s2, v85
	v_add_u32_e32 v89, s2, v83
	v_add_u32_e32 v90, s96, v83
	s_add_i32 s96, s96, 0x3000
	s_cmp_eq_u32 s96, 0x1e800
	s_cselect_b32 s96, 0x20200, s96
	s_cmp_eq_u32 s96, 0x23200
	s_cselect_b32 s96, 0x12800, s96
	v_add_u32_e32 v88, s96, v83
	s_setprio 3
	.p2align 6
